# grid barrier: agent-scope L1 invalidate issued before the release spin / right after the leader write-back instead of after the release (on O2 selection rewrite)
# speedup vs baseline: 1.0092x; 1.0092x over previous
; __device__ __forceinline__ unsigned xb_ld(unsigned* p)              { return __hip_atomic_load(p, __ATOMIC_RELAXED, __HIP_MEMORY_SCOPE_AGENT); }
; __device__ __forceinline__ unsigned xb_add(unsigned* p, unsigned v) { return __hip_atomic_fetch_add(p, v, __ATOMIC_RELAXED, __HIP_MEMORY_SCOPE_AGENT); }
; #define XB_SPIN(cond, bar) do { unsigned _sp = 0; while (cond) { __builtin_amdgcn_s_sleep(1); \
;     if ((++_sp & 255u) == 0u) { if (xb_ld(&(bar)[XB_TMO])) break; if (_sp > XB_SPIN_CAP) { atomicAdd(&(bar)[XB_TMO], 1u); break; } } } } while (0)
; __device__ __forceinline__ void xcd_barrier(const XcdBarrier& b) {
;     ...
;         const unsigned old = xb_add(&bar[XB_XSUB(b.x)], 1u);
;         const unsigned gen = old / nloc;
;         if (old + 1u == (gen + 1u) * nloc) {
;             __builtin_amdgcn_fence(__ATOMIC_RELEASE, "agent");
;             asm volatile("s_waitcnt vmcnt(0)" ::: "memory");
;             const unsigned og = xb_add(&bar[XB_TOP], 1u);
;             const unsigned tg = og / nx;
;             if (og + 1u == (tg + 1u) * nx) xb_add(&bar[XB_TOPGEN], 1u);
;             else XB_SPIN(xb_ld(&bar[XB_TOPGEN]) == tg, bar);
;             __builtin_amdgcn_fence(__ATOMIC_ACQUIRE, "agent");
;             xb_add(&bar[XB_XGEN(b.x)], 1u);
;             asm volatile("s_waitcnt vmcnt(0)" ::: "memory");
;         } else {
;             XB_SPIN(xb_ld(&bar[XB_XGEN(b.x)]) == gen, bar);
.LBB0_1587:
	s_or_b64 exec, exec, s[8:9]
	v_cvt_f32_u32_e32 v4, v2
	s_waitcnt vmcnt(0)
	v_readfirstlane_b32 s6, v3
	v_sub_u32_e32 v3, 0, v2
	v_rcp_iflag_f32_e32 v4, v4
	v_add_u32_e32 v5, s6, v1
	v_mul_f32_e32 v4, 0x4f7ffffe, v4
	v_cvt_u32_f32_e32 v4, v4
	v_mul_lo_u32 v1, v3, v4
	v_mul_hi_u32 v1, v4, v1
	v_add_u32_e32 v1, v4, v1
	v_mul_hi_u32 v1, v5, v1
	v_mul_lo_u32 v3, v1, v2
	v_sub_u32_e32 v3, v5, v3
	v_add_u32_e32 v4, 1, v1
	v_cmp_ge_u32_e32 vcc, v3, v2
	s_nop 1
	v_cndmask_b32_e32 v1, v1, v4, vcc
	v_sub_u32_e32 v4, v3, v2
	v_cndmask_b32_e32 v3, v3, v4, vcc
	v_add_u32_e32 v4, 1, v1
	v_cmp_ge_u32_e32 vcc, v3, v2
	v_add_u32_e32 v3, 1, v5
	s_nop 0
	v_cndmask_b32_e32 v1, v1, v4, vcc
	v_mul_lo_u32 v4, v2, v1
	v_add_u32_e32 v2, v4, v2
	v_cmp_ne_u32_e32 vcc, v3, v2
	s_and_saveexec_b64 s[6:7], vcc
	s_xor_b64 s[6:7], exec, s[6:7]
	s_cbranch_execz .LBB0_1601
	s_waitcnt lgkmcnt(0)
	v_mov_b32_e32 v0, 0x2000
	buffer_inv sc1
	global_load_dword v0, v0, s[4:5] offset:1024 sc1
	s_add_u32 s12, s4, 0x2400
	s_addc_u32 s13, s5, 0
	s_waitcnt vmcnt(0)
	v_cmp_eq_u32_e32 vcc, v0, v1
	s_and_saveexec_b64 s[8:9], vcc
	s_cbranch_execz .LBB0_1600
	s_add_u32 s10, s2, 0x17900200
	s_addc_u32 s11, s3, 0
	s_mov_b32 s24, 1
	s_mov_b64 s[14:15], 0
	v_mov_b32_e32 v0, 0
	s_branch .LBB0_1591

; __device__ __forceinline__ unsigned xb_ld(unsigned* p)              { return __hip_atomic_load(p, __ATOMIC_RELAXED, __HIP_MEMORY_SCOPE_AGENT); }
; __device__ __forceinline__ unsigned xb_add(unsigned* p, unsigned v) { return __hip_atomic_fetch_add(p, v, __ATOMIC_RELAXED, __HIP_MEMORY_SCOPE_AGENT); }
; #define XB_SPIN(cond, bar) do { unsigned _sp = 0; while (cond) { __builtin_amdgcn_s_sleep(1); \
;     if ((++_sp & 255u) == 0u) { if (xb_ld(&(bar)[XB_TMO])) break; if (_sp > XB_SPIN_CAP) { atomicAdd(&(bar)[XB_TMO], 1u); break; } } } } while (0)
; __device__ __forceinline__ void xcd_barrier(const XcdBarrier& b) {
;     ...
;             __builtin_amdgcn_fence(__ATOMIC_RELEASE, "agent");
;             asm volatile("s_waitcnt vmcnt(0)" ::: "memory");
;             const unsigned og = xb_add(&bar[XB_TOP], 1u);
;             const unsigned tg = og / nx;
;             if (og + 1u == (tg + 1u) * nx) xb_add(&bar[XB_TOPGEN], 1u);
;             else XB_SPIN(xb_ld(&bar[XB_TOPGEN]) == tg, bar);
;             __builtin_amdgcn_fence(__ATOMIC_ACQUIRE, "agent");
;             xb_add(&bar[XB_XGEN(b.x)], 1u);
;             asm volatile("s_waitcnt vmcnt(0)" ::: "memory");
;         } else {
;             XB_SPIN(xb_ld(&bar[XB_XGEN(b.x)]) == gen, bar);
;             __builtin_amdgcn_fence(__ATOMIC_ACQUIRE, "agent");
;             asm volatile("s_waitcnt vmcnt(0)" ::: "memory");
.LBB0_1600:
	s_or_b64 exec, exec, s[8:9]
	s_waitcnt vmcnt(0)
	s_waitcnt vmcnt(0)
.LBB0_1601:
	s_andn2_saveexec_b64 s[6:7], s[6:7]
	s_cbranch_execz .LBB0_1621
	s_mov_b64 s[6:7], exec
	buffer_wbl2 sc1
	s_waitcnt lgkmcnt(0)
	s_waitcnt vmcnt(0)
	buffer_inv sc1
	v_mbcnt_lo_u32_b32 v1, s6, 0
	v_mbcnt_hi_u32_b32 v1, s7, v1
	v_cmp_eq_u32_e32 vcc, 0, v1
	s_and_saveexec_b64 s[8:9], vcc
	s_cbranch_execz .LBB0_1604
	s_bcnt1_i32_b64 s6, s[6:7]
	v_mov_b32_e32 v2, 0x17903000
	v_mov_b32_e32 v3, s6
	global_atomic_add v2, v2, v3, s[2:3] offset:1024 sc0

; __device__ __forceinline__ unsigned xb_ld(unsigned* p)              { return __hip_atomic_load(p, __ATOMIC_RELAXED, __HIP_MEMORY_SCOPE_AGENT); }
; __device__ __forceinline__ unsigned xb_add(unsigned* p, unsigned v) { return __hip_atomic_fetch_add(p, v, __ATOMIC_RELAXED, __HIP_MEMORY_SCOPE_AGENT); }
; #define XB_SPIN(cond, bar) do { unsigned _sp = 0; while (cond) { __builtin_amdgcn_s_sleep(1); \
;     if ((++_sp & 255u) == 0u) { if (xb_ld(&(bar)[XB_TMO])) break; if (_sp > XB_SPIN_CAP) { atomicAdd(&(bar)[XB_TMO], 1u); break; } } } } while (0)
; __device__ __forceinline__ void xcd_barrier(const XcdBarrier& b) {
;     ...
;             if (og + 1u == (tg + 1u) * nx) xb_add(&bar[XB_TOPGEN], 1u);
;             else XB_SPIN(xb_ld(&bar[XB_TOPGEN]) == tg, bar);
;             __builtin_amdgcn_fence(__ATOMIC_ACQUIRE, "agent");
;             xb_add(&bar[XB_XGEN(b.x)], 1u);
;             asm volatile("s_waitcnt vmcnt(0)" ::: "memory");
.LBB0_1618:
	s_or_b64 exec, exec, s[2:3]
	s_mov_b64 s[2:3], exec
	v_mbcnt_lo_u32_b32 v0, s2, 0
	v_mbcnt_hi_u32_b32 v0, s3, v0
	v_cmp_eq_u32_e32 vcc, 0, v0
	s_waitcnt vmcnt(0)
	s_and_saveexec_b64 s[6:7], vcc
	s_cbranch_execz .LBB0_1620
	s_bcnt1_i32_b64 s2, s[2:3]
	v_mov_b32_e32 v0, 0x2000
	v_mov_b32_e32 v1, s2
	global_atomic_add v0, v1, s[4:5] offset:1024

; __device__ __forceinline__ unsigned xb_ld(unsigned* p)              { return __hip_atomic_load(p, __ATOMIC_RELAXED, __HIP_MEMORY_SCOPE_AGENT); }
; __device__ __forceinline__ unsigned xb_add(unsigned* p, unsigned v) { return __hip_atomic_fetch_add(p, v, __ATOMIC_RELAXED, __HIP_MEMORY_SCOPE_AGENT); }
; #define XB_SPIN(cond, bar) do { unsigned _sp = 0; while (cond) { __builtin_amdgcn_s_sleep(1); \
;     if ((++_sp & 255u) == 0u) { if (xb_ld(&(bar)[XB_TMO])) break; if (_sp > XB_SPIN_CAP) { atomicAdd(&(bar)[XB_TMO], 1u); break; } } } } while (0)
; __device__ __forceinline__ void xcd_barrier(const XcdBarrier& b) {
;     ...
;         const unsigned old = xb_add(&bar[XB_XSUB(b.x)], 1u);
;         const unsigned gen = old / nloc;
;         if (old + 1u == (gen + 1u) * nloc) {
;             __builtin_amdgcn_fence(__ATOMIC_RELEASE, "agent");
;             asm volatile("s_waitcnt vmcnt(0)" ::: "memory");
;             const unsigned og = xb_add(&bar[XB_TOP], 1u);
;             const unsigned tg = og / nx;
;             if (og + 1u == (tg + 1u) * nx) xb_add(&bar[XB_TOPGEN], 1u);
;             else XB_SPIN(xb_ld(&bar[XB_TOPGEN]) == tg, bar);
;             __builtin_amdgcn_fence(__ATOMIC_ACQUIRE, "agent");
;             xb_add(&bar[XB_XGEN(b.x)], 1u);
;             asm volatile("s_waitcnt vmcnt(0)" ::: "memory");
;         } else {
;             XB_SPIN(xb_ld(&bar[XB_XGEN(b.x)]) == gen, bar);
.LBB0_3108:
	s_or_b64 exec, exec, s[14:15]
	v_cvt_f32_u32_e32 v5, v3
	s_waitcnt vmcnt(0)
	v_readfirstlane_b32 s10, v4
	v_sub_u32_e32 v4, 0, v3
	v_rcp_iflag_f32_e32 v5, v5
	v_add_u32_e32 v6, s10, v1
	v_mul_f32_e32 v5, 0x4f7ffffe, v5
	v_cvt_u32_f32_e32 v5, v5
	v_mul_lo_u32 v1, v4, v5
	v_mul_hi_u32 v1, v5, v1
	v_add_u32_e32 v1, v5, v1
	v_mul_hi_u32 v1, v6, v1
	v_mul_lo_u32 v4, v1, v3
	v_sub_u32_e32 v4, v6, v4
	v_add_u32_e32 v5, 1, v1
	v_cmp_ge_u32_e32 vcc, v4, v3
	s_nop 1
	v_cndmask_b32_e32 v1, v1, v5, vcc
	v_sub_u32_e32 v5, v4, v3
	v_cndmask_b32_e32 v4, v4, v5, vcc
	v_add_u32_e32 v5, 1, v1
	v_cmp_ge_u32_e32 vcc, v4, v3
	v_add_u32_e32 v4, 1, v6
	s_nop 0
	v_cndmask_b32_e32 v1, v1, v5, vcc
	v_mul_lo_u32 v5, v3, v1
	v_add_u32_e32 v3, v5, v3
	v_cmp_ne_u32_e32 vcc, v4, v3
	s_and_saveexec_b64 s[10:11], vcc
	s_xor_b64 s[10:11], exec, s[10:11]
	s_cbranch_execz .LBB0_3122
	s_waitcnt lgkmcnt(0)
	buffer_inv sc1
	global_load_dword v2, v241, s[8:9] offset:1024 sc1
	s_add_u32 s18, s8, 0x2400
	s_addc_u32 s19, s9, 0
	s_waitcnt vmcnt(0)
	v_cmp_eq_u32_e32 vcc, v2, v1
	s_and_saveexec_b64 s[14:15], vcc
	s_cbranch_execz .LBB0_3121
	s_add_u32 s16, s4, 0x17900200
	s_addc_u32 s17, s5, 0
	s_mov_b32 s30, 1
	s_mov_b64 s[20:21], 0
	s_branch .LBB0_3112

; __device__ __forceinline__ unsigned xb_ld(unsigned* p)              { return __hip_atomic_load(p, __ATOMIC_RELAXED, __HIP_MEMORY_SCOPE_AGENT); }
; __device__ __forceinline__ unsigned xb_add(unsigned* p, unsigned v) { return __hip_atomic_fetch_add(p, v, __ATOMIC_RELAXED, __HIP_MEMORY_SCOPE_AGENT); }
; #define XB_SPIN(cond, bar) do { unsigned _sp = 0; while (cond) { __builtin_amdgcn_s_sleep(1); \
;     if ((++_sp & 255u) == 0u) { if (xb_ld(&(bar)[XB_TMO])) break; if (_sp > XB_SPIN_CAP) { atomicAdd(&(bar)[XB_TMO], 1u); break; } } } } while (0)
; __device__ __forceinline__ void xcd_barrier(const XcdBarrier& b) {
;     ...
;             __builtin_amdgcn_fence(__ATOMIC_RELEASE, "agent");
;             asm volatile("s_waitcnt vmcnt(0)" ::: "memory");
;             const unsigned og = xb_add(&bar[XB_TOP], 1u);
;             const unsigned tg = og / nx;
;             if (og + 1u == (tg + 1u) * nx) xb_add(&bar[XB_TOPGEN], 1u);
;             else XB_SPIN(xb_ld(&bar[XB_TOPGEN]) == tg, bar);
;             __builtin_amdgcn_fence(__ATOMIC_ACQUIRE, "agent");
;             xb_add(&bar[XB_XGEN(b.x)], 1u);
;             asm volatile("s_waitcnt vmcnt(0)" ::: "memory");
;         } else {
;             XB_SPIN(xb_ld(&bar[XB_XGEN(b.x)]) == gen, bar);
;             __builtin_amdgcn_fence(__ATOMIC_ACQUIRE, "agent");
;             asm volatile("s_waitcnt vmcnt(0)" ::: "memory");
.LBB0_3121:
	s_or_b64 exec, exec, s[14:15]
	s_waitcnt vmcnt(0)
	s_waitcnt vmcnt(0)
.LBB0_3122:
	s_andn2_saveexec_b64 s[10:11], s[10:11]
	s_cbranch_execz .LBB0_3142
	s_mov_b64 s[10:11], exec
	buffer_wbl2 sc1
	s_waitcnt lgkmcnt(0)
	s_waitcnt vmcnt(0)
	buffer_inv sc1
	v_mbcnt_lo_u32_b32 v1, s10, 0
	v_mbcnt_hi_u32_b32 v1, s11, v1
	v_cmp_eq_u32_e32 vcc, 0, v1
	s_and_saveexec_b64 s[14:15], vcc
	s_cbranch_execz .LBB0_3125
	s_bcnt1_i32_b64 s10, s[10:11]
	v_mov_b32_e32 v3, s10
	v_mov_b32_e32 v4, 0x17903000
	global_atomic_add v3, v4, v3, s[4:5] offset:1024 sc0

; __device__ __forceinline__ unsigned xb_ld(unsigned* p)              { return __hip_atomic_load(p, __ATOMIC_RELAXED, __HIP_MEMORY_SCOPE_AGENT); }
; __device__ __forceinline__ unsigned xb_add(unsigned* p, unsigned v) { return __hip_atomic_fetch_add(p, v, __ATOMIC_RELAXED, __HIP_MEMORY_SCOPE_AGENT); }
; #define XB_SPIN(cond, bar) do { unsigned _sp = 0; while (cond) { __builtin_amdgcn_s_sleep(1); \
;     if ((++_sp & 255u) == 0u) { if (xb_ld(&(bar)[XB_TMO])) break; if (_sp > XB_SPIN_CAP) { atomicAdd(&(bar)[XB_TMO], 1u); break; } } } } while (0)
; __device__ __forceinline__ void xcd_barrier(const XcdBarrier& b) {
;     ...
;             if (og + 1u == (tg + 1u) * nx) xb_add(&bar[XB_TOPGEN], 1u);
;             else XB_SPIN(xb_ld(&bar[XB_TOPGEN]) == tg, bar);
;             __builtin_amdgcn_fence(__ATOMIC_ACQUIRE, "agent");
;             xb_add(&bar[XB_XGEN(b.x)], 1u);
;             asm volatile("s_waitcnt vmcnt(0)" ::: "memory");
.LBB0_3139:
	s_or_b64 exec, exec, s[4:5]
	s_mov_b64 s[4:5], exec
	v_mbcnt_lo_u32_b32 v1, s4, 0
	v_mbcnt_hi_u32_b32 v1, s5, v1
	v_cmp_eq_u32_e32 vcc, 0, v1
	s_waitcnt vmcnt(0)
	s_and_saveexec_b64 s[10:11], vcc
	s_cbranch_execz .LBB0_3141
	s_bcnt1_i32_b64 s4, s[4:5]
	v_mov_b32_e32 v1, s4
	global_atomic_add v241, v1, s[8:9] offset:1024

; __device__ __forceinline__ unsigned xb_ld(unsigned* p)              { return __hip_atomic_load(p, __ATOMIC_RELAXED, __HIP_MEMORY_SCOPE_AGENT); }
; __device__ __forceinline__ unsigned xb_add(unsigned* p, unsigned v) { return __hip_atomic_fetch_add(p, v, __ATOMIC_RELAXED, __HIP_MEMORY_SCOPE_AGENT); }
; #define XB_SPIN(cond, bar) do { unsigned _sp = 0; while (cond) { __builtin_amdgcn_s_sleep(1); \
;     if ((++_sp & 255u) == 0u) { if (xb_ld(&(bar)[XB_TMO])) break; if (_sp > XB_SPIN_CAP) { atomicAdd(&(bar)[XB_TMO], 1u); break; } } } } while (0)
; __device__ __forceinline__ void xcd_barrier(const XcdBarrier& b) {
;     ...
;         const unsigned old = xb_add(&bar[XB_XSUB(b.x)], 1u);
;         const unsigned gen = old / nloc;
;         if (old + 1u == (gen + 1u) * nloc) {
;             __builtin_amdgcn_fence(__ATOMIC_RELEASE, "agent");
;             asm volatile("s_waitcnt vmcnt(0)" ::: "memory");
;             const unsigned og = xb_add(&bar[XB_TOP], 1u);
;             const unsigned tg = og / nx;
;             if (og + 1u == (tg + 1u) * nx) xb_add(&bar[XB_TOPGEN], 1u);
;             else XB_SPIN(xb_ld(&bar[XB_TOPGEN]) == tg, bar);
;             __builtin_amdgcn_fence(__ATOMIC_ACQUIRE, "agent");
;             xb_add(&bar[XB_XGEN(b.x)], 1u);
;             asm volatile("s_waitcnt vmcnt(0)" ::: "memory");
;         } else {
;             XB_SPIN(xb_ld(&bar[XB_XGEN(b.x)]) == gen, bar);
.LBB0_3290:
	s_or_b64 exec, exec, s[10:11]
	v_cvt_f32_u32_e32 v5, v3
	s_waitcnt vmcnt(0)
	v_readfirstlane_b32 s8, v4
	v_sub_u32_e32 v4, 0, v3
	v_rcp_iflag_f32_e32 v5, v5
	v_add_u32_e32 v6, s8, v1
	v_mul_f32_e32 v5, 0x4f7ffffe, v5
	v_cvt_u32_f32_e32 v5, v5
	v_mul_lo_u32 v1, v4, v5
	v_mul_hi_u32 v1, v5, v1
	v_add_u32_e32 v1, v5, v1
	v_mul_hi_u32 v1, v6, v1
	v_mul_lo_u32 v4, v1, v3
	v_sub_u32_e32 v4, v6, v4
	v_add_u32_e32 v5, 1, v1
	v_cmp_ge_u32_e32 vcc, v4, v3
	s_nop 1
	v_cndmask_b32_e32 v1, v1, v5, vcc
	v_sub_u32_e32 v5, v4, v3
	v_cndmask_b32_e32 v4, v4, v5, vcc
	v_add_u32_e32 v5, 1, v1
	v_cmp_ge_u32_e32 vcc, v4, v3
	v_add_u32_e32 v4, 1, v6
	s_nop 0
	v_cndmask_b32_e32 v1, v1, v5, vcc
	v_mul_lo_u32 v5, v3, v1
	v_add_u32_e32 v3, v5, v3
	v_cmp_ne_u32_e32 vcc, v4, v3
	s_and_saveexec_b64 s[8:9], vcc
	s_xor_b64 s[8:9], exec, s[8:9]
	s_cbranch_execz .LBB0_3304
	s_waitcnt lgkmcnt(0)
	buffer_inv sc1
	global_load_dword v2, v241, s[6:7] offset:1024 sc1
	s_add_u32 s16, s6, 0x2400
	s_addc_u32 s17, s7, 0
	s_waitcnt vmcnt(0)
	v_cmp_eq_u32_e32 vcc, v2, v1
	s_and_saveexec_b64 s[10:11], vcc
	s_cbranch_execz .LBB0_3303
	s_add_u32 s14, s4, 0x17900200
	s_addc_u32 s15, s5, 0
	s_mov_b32 s28, 1
	s_mov_b64 s[18:19], 0
	s_branch .LBB0_3294

; __device__ __forceinline__ unsigned xb_ld(unsigned* p)              { return __hip_atomic_load(p, __ATOMIC_RELAXED, __HIP_MEMORY_SCOPE_AGENT); }
; __device__ __forceinline__ unsigned xb_add(unsigned* p, unsigned v) { return __hip_atomic_fetch_add(p, v, __ATOMIC_RELAXED, __HIP_MEMORY_SCOPE_AGENT); }
; #define XB_SPIN(cond, bar) do { unsigned _sp = 0; while (cond) { __builtin_amdgcn_s_sleep(1); \
;     if ((++_sp & 255u) == 0u) { if (xb_ld(&(bar)[XB_TMO])) break; if (_sp > XB_SPIN_CAP) { atomicAdd(&(bar)[XB_TMO], 1u); break; } } } } while (0)
; __device__ __forceinline__ void xcd_barrier(const XcdBarrier& b) {
;     ...
;             __builtin_amdgcn_fence(__ATOMIC_RELEASE, "agent");
;             asm volatile("s_waitcnt vmcnt(0)" ::: "memory");
;             const unsigned og = xb_add(&bar[XB_TOP], 1u);
;             const unsigned tg = og / nx;
;             if (og + 1u == (tg + 1u) * nx) xb_add(&bar[XB_TOPGEN], 1u);
;             else XB_SPIN(xb_ld(&bar[XB_TOPGEN]) == tg, bar);
;             __builtin_amdgcn_fence(__ATOMIC_ACQUIRE, "agent");
;             xb_add(&bar[XB_XGEN(b.x)], 1u);
;             asm volatile("s_waitcnt vmcnt(0)" ::: "memory");
;         } else {
;             XB_SPIN(xb_ld(&bar[XB_XGEN(b.x)]) == gen, bar);
;             __builtin_amdgcn_fence(__ATOMIC_ACQUIRE, "agent");
;             asm volatile("s_waitcnt vmcnt(0)" ::: "memory");
.LBB0_3303:
	s_or_b64 exec, exec, s[10:11]
	s_waitcnt vmcnt(0)
	s_waitcnt vmcnt(0)
.LBB0_3304:
	s_andn2_saveexec_b64 s[8:9], s[8:9]
	s_cbranch_execz .LBB0_3324
	s_mov_b64 s[8:9], exec
	buffer_wbl2 sc1
	s_waitcnt lgkmcnt(0)
	s_waitcnt vmcnt(0)
	buffer_inv sc1
	v_mbcnt_lo_u32_b32 v1, s8, 0
	v_mbcnt_hi_u32_b32 v1, s9, v1
	v_cmp_eq_u32_e32 vcc, 0, v1
	s_and_saveexec_b64 s[10:11], vcc
	s_cbranch_execz .LBB0_3307
	s_bcnt1_i32_b64 s8, s[8:9]
	v_mov_b32_e32 v3, s8
	v_mov_b32_e32 v4, 0x17903000
	global_atomic_add v3, v4, v3, s[4:5] offset:1024 sc0

; __device__ __forceinline__ unsigned xb_ld(unsigned* p)              { return __hip_atomic_load(p, __ATOMIC_RELAXED, __HIP_MEMORY_SCOPE_AGENT); }
; __device__ __forceinline__ unsigned xb_add(unsigned* p, unsigned v) { return __hip_atomic_fetch_add(p, v, __ATOMIC_RELAXED, __HIP_MEMORY_SCOPE_AGENT); }
; #define XB_SPIN(cond, bar) do { unsigned _sp = 0; while (cond) { __builtin_amdgcn_s_sleep(1); \
;     if ((++_sp & 255u) == 0u) { if (xb_ld(&(bar)[XB_TMO])) break; if (_sp > XB_SPIN_CAP) { atomicAdd(&(bar)[XB_TMO], 1u); break; } } } } while (0)
; __device__ __forceinline__ void xcd_barrier(const XcdBarrier& b) {
;     ...
;             if (og + 1u == (tg + 1u) * nx) xb_add(&bar[XB_TOPGEN], 1u);
;             else XB_SPIN(xb_ld(&bar[XB_TOPGEN]) == tg, bar);
;             __builtin_amdgcn_fence(__ATOMIC_ACQUIRE, "agent");
;             xb_add(&bar[XB_XGEN(b.x)], 1u);
;             asm volatile("s_waitcnt vmcnt(0)" ::: "memory");
.LBB0_3321:
	s_or_b64 exec, exec, s[4:5]
	s_mov_b64 s[4:5], exec
	v_mbcnt_lo_u32_b32 v1, s4, 0
	v_mbcnt_hi_u32_b32 v1, s5, v1
	v_cmp_eq_u32_e32 vcc, 0, v1
	s_waitcnt vmcnt(0)
	s_and_saveexec_b64 s[8:9], vcc
	s_cbranch_execz .LBB0_3323
	s_bcnt1_i32_b64 s4, s[4:5]
	v_mov_b32_e32 v1, s4
	global_atomic_add v241, v1, s[6:7] offset:1024

; __device__ __forceinline__ unsigned xb_ld(unsigned* p)              { return __hip_atomic_load(p, __ATOMIC_RELAXED, __HIP_MEMORY_SCOPE_AGENT); }
; __device__ __forceinline__ unsigned xb_add(unsigned* p, unsigned v) { return __hip_atomic_fetch_add(p, v, __ATOMIC_RELAXED, __HIP_MEMORY_SCOPE_AGENT); }
; #define XB_SPIN(cond, bar) do { unsigned _sp = 0; while (cond) { __builtin_amdgcn_s_sleep(1); \
;     if ((++_sp & 255u) == 0u) { if (xb_ld(&(bar)[XB_TMO])) break; if (_sp > XB_SPIN_CAP) { atomicAdd(&(bar)[XB_TMO], 1u); break; } } } } while (0)
; __device__ __forceinline__ void xcd_barrier(const XcdBarrier& b) {
;     ...
;         const unsigned old = xb_add(&bar[XB_XSUB(b.x)], 1u);
;         const unsigned gen = old / nloc;
;         if (old + 1u == (gen + 1u) * nloc) {
;             __builtin_amdgcn_fence(__ATOMIC_RELEASE, "agent");
;             asm volatile("s_waitcnt vmcnt(0)" ::: "memory");
;             const unsigned og = xb_add(&bar[XB_TOP], 1u);
;             const unsigned tg = og / nx;
;             if (og + 1u == (tg + 1u) * nx) xb_add(&bar[XB_TOPGEN], 1u);
;             else XB_SPIN(xb_ld(&bar[XB_TOPGEN]) == tg, bar);
;             __builtin_amdgcn_fence(__ATOMIC_ACQUIRE, "agent");
;             xb_add(&bar[XB_XGEN(b.x)], 1u);
;             asm volatile("s_waitcnt vmcnt(0)" ::: "memory");
;         } else {
;             XB_SPIN(xb_ld(&bar[XB_XGEN(b.x)]) == gen, bar);
.LBB0_3371:
	s_or_b64 exec, exec, s[10:11]
	v_cvt_f32_u32_e32 v5, v3
	s_waitcnt vmcnt(0)
	v_readfirstlane_b32 s8, v4
	v_sub_u32_e32 v4, 0, v3
	v_rcp_iflag_f32_e32 v5, v5
	v_add_u32_e32 v6, s8, v1
	v_mul_f32_e32 v5, 0x4f7ffffe, v5
	v_cvt_u32_f32_e32 v5, v5
	v_mul_lo_u32 v1, v4, v5
	v_mul_hi_u32 v1, v5, v1
	v_add_u32_e32 v1, v5, v1
	v_mul_hi_u32 v1, v6, v1
	v_mul_lo_u32 v4, v1, v3
	v_sub_u32_e32 v4, v6, v4
	v_add_u32_e32 v5, 1, v1
	v_cmp_ge_u32_e32 vcc, v4, v3
	s_nop 1
	v_cndmask_b32_e32 v1, v1, v5, vcc
	v_sub_u32_e32 v5, v4, v3
	v_cndmask_b32_e32 v4, v4, v5, vcc
	v_add_u32_e32 v5, 1, v1
	v_cmp_ge_u32_e32 vcc, v4, v3
	v_add_u32_e32 v4, 1, v6
	s_nop 0
	v_cndmask_b32_e32 v1, v1, v5, vcc
	v_mul_lo_u32 v5, v3, v1
	v_add_u32_e32 v3, v5, v3
	v_cmp_ne_u32_e32 vcc, v4, v3
	s_and_saveexec_b64 s[8:9], vcc
	s_xor_b64 s[8:9], exec, s[8:9]
	s_cbranch_execz .LBB0_3385
	s_waitcnt lgkmcnt(0)
	buffer_inv sc1
	global_load_dword v2, v241, s[6:7] offset:1024 sc1
	s_add_u32 s14, s6, 0x2400
	s_addc_u32 s15, s7, 0
	s_waitcnt vmcnt(0)
	v_cmp_eq_u32_e32 vcc, v2, v1
	s_and_saveexec_b64 s[10:11], vcc
	s_cbranch_execz .LBB0_3384
	s_add_u32 s12, s4, 0x17900200
	s_addc_u32 s13, s5, 0
	s_mov_b32 s26, 1
	s_mov_b64 s[16:17], 0
	s_branch .LBB0_3375

; __device__ __forceinline__ unsigned xb_ld(unsigned* p)              { return __hip_atomic_load(p, __ATOMIC_RELAXED, __HIP_MEMORY_SCOPE_AGENT); }
; __device__ __forceinline__ unsigned xb_add(unsigned* p, unsigned v) { return __hip_atomic_fetch_add(p, v, __ATOMIC_RELAXED, __HIP_MEMORY_SCOPE_AGENT); }
; #define XB_SPIN(cond, bar) do { unsigned _sp = 0; while (cond) { __builtin_amdgcn_s_sleep(1); \
;     if ((++_sp & 255u) == 0u) { if (xb_ld(&(bar)[XB_TMO])) break; if (_sp > XB_SPIN_CAP) { atomicAdd(&(bar)[XB_TMO], 1u); break; } } } } while (0)
; __device__ __forceinline__ void xcd_barrier(const XcdBarrier& b) {
;     ...
;         const unsigned old = xb_add(&bar[XB_XSUB(b.x)], 1u);
;         const unsigned gen = old / nloc;
;         if (old + 1u == (gen + 1u) * nloc) {
;             __builtin_amdgcn_fence(__ATOMIC_RELEASE, "agent");
;             asm volatile("s_waitcnt vmcnt(0)" ::: "memory");
;             const unsigned og = xb_add(&bar[XB_TOP], 1u);
;             const unsigned tg = og / nx;
;             if (og + 1u == (tg + 1u) * nx) xb_add(&bar[XB_TOPGEN], 1u);
;             else XB_SPIN(xb_ld(&bar[XB_TOPGEN]) == tg, bar);
;             __builtin_amdgcn_fence(__ATOMIC_ACQUIRE, "agent");
;             xb_add(&bar[XB_XGEN(b.x)], 1u);
;             asm volatile("s_waitcnt vmcnt(0)" ::: "memory");
;         } else {
;             XB_SPIN(xb_ld(&bar[XB_XGEN(b.x)]) == gen, bar);
.LBB0_3474:
	s_or_b64 exec, exec, s[8:9]
	v_cvt_f32_u32_e32 v5, v3
	s_waitcnt vmcnt(0)
	v_readfirstlane_b32 s6, v4
	v_sub_u32_e32 v4, 0, v3
	v_rcp_iflag_f32_e32 v5, v5
	v_add_u32_e32 v6, s6, v1
	v_mul_f32_e32 v5, 0x4f7ffffe, v5
	v_cvt_u32_f32_e32 v5, v5
	v_mul_lo_u32 v1, v4, v5
	v_mul_hi_u32 v1, v5, v1
	v_add_u32_e32 v1, v5, v1
	v_mul_hi_u32 v1, v6, v1
	v_mul_lo_u32 v4, v1, v3
	v_sub_u32_e32 v4, v6, v4
	v_add_u32_e32 v5, 1, v1
	v_cmp_ge_u32_e32 vcc, v4, v3
	s_nop 1
	v_cndmask_b32_e32 v1, v1, v5, vcc
	v_sub_u32_e32 v5, v4, v3
	v_cndmask_b32_e32 v4, v4, v5, vcc
	v_add_u32_e32 v5, 1, v1
	v_cmp_ge_u32_e32 vcc, v4, v3
	v_add_u32_e32 v4, 1, v6
	s_nop 0
	v_cndmask_b32_e32 v1, v1, v5, vcc
	v_mul_lo_u32 v5, v3, v1
	v_add_u32_e32 v3, v5, v3
	v_cmp_ne_u32_e32 vcc, v4, v3
	s_and_saveexec_b64 s[6:7], vcc
	s_xor_b64 s[6:7], exec, s[6:7]
	s_cbranch_execz .LBB0_3488
	s_waitcnt lgkmcnt(0)
	buffer_inv sc1
	global_load_dword v2, v241, s[4:5] offset:1024 sc1
	s_add_u32 s12, s4, 0x2400
	s_addc_u32 s13, s5, 0
	s_waitcnt vmcnt(0)
	v_cmp_eq_u32_e32 vcc, v2, v1
	s_and_saveexec_b64 s[8:9], vcc
	s_cbranch_execz .LBB0_3487
	s_add_u32 s10, s2, 0x17900200
	s_addc_u32 s11, s3, 0
	s_mov_b32 s24, 1
	s_mov_b64 s[14:15], 0
	s_branch .LBB0_3478

; __device__ __forceinline__ unsigned xb_add(unsigned* p, unsigned v) { return __hip_atomic_fetch_add(p, v, __ATOMIC_RELAXED, __HIP_MEMORY_SCOPE_AGENT); }
; __device__ __forceinline__ void xcd_barrier(const XcdBarrier& b) {
;     ...
;             __builtin_amdgcn_fence(__ATOMIC_RELEASE, "agent");
;             asm volatile("s_waitcnt vmcnt(0)" ::: "memory");
;             const unsigned og = xb_add(&bar[XB_TOP], 1u);
.LBB0_3488:
	s_andn2_saveexec_b64 s[6:7], s[6:7]
	s_cbranch_execz .LBB0_3508
	s_mov_b64 s[6:7], exec
	buffer_wbl2 sc1
	s_waitcnt lgkmcnt(0)
	s_waitcnt vmcnt(0)
	buffer_inv sc1
	v_mbcnt_lo_u32_b32 v1, s6, 0
	v_mbcnt_hi_u32_b32 v1, s7, v1
	v_cmp_eq_u32_e32 vcc, 0, v1
	s_and_saveexec_b64 s[8:9], vcc
	s_cbranch_execz .LBB0_3491
	s_bcnt1_i32_b64 s6, s[6:7]
	v_mov_b32_e32 v3, s6
	v_mov_b32_e32 v4, 0x17903000
	global_atomic_add v3, v4, v3, s[2:3] offset:1024 sc0

; __device__ __forceinline__ unsigned xb_ld(unsigned* p)              { return __hip_atomic_load(p, __ATOMIC_RELAXED, __HIP_MEMORY_SCOPE_AGENT); }
; __device__ __forceinline__ unsigned xb_add(unsigned* p, unsigned v) { return __hip_atomic_fetch_add(p, v, __ATOMIC_RELAXED, __HIP_MEMORY_SCOPE_AGENT); }
; #define XB_SPIN(cond, bar) do { unsigned _sp = 0; while (cond) { __builtin_amdgcn_s_sleep(1); \
;     if ((++_sp & 255u) == 0u) { if (xb_ld(&(bar)[XB_TMO])) break; if (_sp > XB_SPIN_CAP) { atomicAdd(&(bar)[XB_TMO], 1u); break; } } } } while (0)
; __device__ __forceinline__ void xcd_barrier(const XcdBarrier& b) {
;     ...
;             if (og + 1u == (tg + 1u) * nx) xb_add(&bar[XB_TOPGEN], 1u);
;             else XB_SPIN(xb_ld(&bar[XB_TOPGEN]) == tg, bar);
;             __builtin_amdgcn_fence(__ATOMIC_ACQUIRE, "agent");
;             xb_add(&bar[XB_XGEN(b.x)], 1u);
;             asm volatile("s_waitcnt vmcnt(0)" ::: "memory");
.LBB0_3505:
	s_or_b64 exec, exec, s[2:3]
	s_mov_b64 s[2:3], exec
	v_mbcnt_lo_u32_b32 v1, s2, 0
	v_mbcnt_hi_u32_b32 v1, s3, v1
	v_cmp_eq_u32_e32 vcc, 0, v1
	s_waitcnt vmcnt(0)
	s_and_saveexec_b64 s[6:7], vcc
	s_cbranch_execz .LBB0_3507
	s_bcnt1_i32_b64 s2, s[2:3]
	v_mov_b32_e32 v1, s2
	global_atomic_add v241, v1, s[4:5] offset:1024

; __device__ __forceinline__ unsigned xb_add(unsigned* p, unsigned v) { return __hip_atomic_fetch_add(p, v, __ATOMIC_RELAXED, __HIP_MEMORY_SCOPE_AGENT); }
; __device__ __forceinline__ void xcd_barrier(const XcdBarrier& b) {
;     ...
;             __builtin_amdgcn_fence(__ATOMIC_RELEASE, "agent");
;             asm volatile("s_waitcnt vmcnt(0)" ::: "memory");
;             const unsigned og = xb_add(&bar[XB_TOP], 1u);
.LBB0_4986:
	s_mov_b64 s[6:7], exec
	buffer_wbl2 sc1
	s_waitcnt lgkmcnt(0)
	s_waitcnt vmcnt(0)
	buffer_inv sc1
	v_mbcnt_lo_u32_b32 v1, s6, 0
	v_mbcnt_hi_u32_b32 v1, s7, v1
	v_cmp_eq_u32_e32 vcc, 0, v1
	s_and_saveexec_b64 s[8:9], vcc
	s_cbranch_execz .LBB0_4988
	s_bcnt1_i32_b64 s6, s[6:7]
	v_mov_b32_e32 v3, s6
	v_mov_b32_e32 v4, 0x17903000
	global_atomic_add v3, v4, v3, s[2:3] offset:1024 sc0

; __device__ __forceinline__ unsigned xb_ld(unsigned* p)              { return __hip_atomic_load(p, __ATOMIC_RELAXED, __HIP_MEMORY_SCOPE_AGENT); }
; __device__ __forceinline__ unsigned xb_add(unsigned* p, unsigned v) { return __hip_atomic_fetch_add(p, v, __ATOMIC_RELAXED, __HIP_MEMORY_SCOPE_AGENT); }
; #define XB_SPIN(cond, bar) do { unsigned _sp = 0; while (cond) { __builtin_amdgcn_s_sleep(1); \
;     if ((++_sp & 255u) == 0u) { if (xb_ld(&(bar)[XB_TMO])) break; if (_sp > XB_SPIN_CAP) { atomicAdd(&(bar)[XB_TMO], 1u); break; } } } } while (0)
; __device__ __forceinline__ void xcd_barrier(const XcdBarrier& b) {
;     ...
;             if (og + 1u == (tg + 1u) * nx) xb_add(&bar[XB_TOPGEN], 1u);
;             else XB_SPIN(xb_ld(&bar[XB_TOPGEN]) == tg, bar);
;             __builtin_amdgcn_fence(__ATOMIC_ACQUIRE, "agent");
;             xb_add(&bar[XB_XGEN(b.x)], 1u);
;             asm volatile("s_waitcnt vmcnt(0)" ::: "memory");
.LBB0_5002:
	s_or_b64 exec, exec, s[2:3]
	s_mov_b64 s[2:3], exec
	v_mbcnt_lo_u32_b32 v1, s2, 0
	v_mbcnt_hi_u32_b32 v1, s3, v1
	v_cmp_eq_u32_e32 vcc, 0, v1
	s_waitcnt vmcnt(0)
	s_and_saveexec_b64 s[6:7], vcc
	s_cbranch_execnz .LBB0_5003
	s_getpc_b64 s[98:99]
